# non-temporal hint on the f32 residual (x) loads and stores of the mode-1 GEMM epilogue (touched once per phase)
# speedup vs baseline: 1.0046x; 1.0046x over previous
.LBB0_540:
	s_andn2_b64 vcc, exec, s[10:11]
	s_cbranch_vccnz .LBB0_514
	v_lshl_or_b32 v138, s25, 8, v187
	v_lshlrev_b64 v[136:137], 12, v[162:163]
	v_ashrrev_i32_e32 v139, 31, v138
	v_lshl_add_u64 v[140:141], s[16:17], 0, v[136:137]
	v_lshlrev_b64 v[136:137], 2, v[138:139]
	v_ashrrev_i32_e32 v135, 31, v134
	v_lshl_add_u64 v[142:143], v[140:141], 0, v[136:137]
	v_lshlrev_b64 v[140:141], 12, v[134:135]
	v_lshl_add_u64 v[140:141], s[16:17], 0, v[140:141]
	global_load_dwordx4 v[190:193], v[142:143], off nt
	v_lshl_add_u64 v[140:141], v[140:141], 0, v[136:137]
	global_load_dwordx4 v[194:197], v[140:141], off nt
	global_load_dwordx4 v[198:201], v[142:143], off offset:64 nt
	global_load_dwordx4 v[202:205], v[140:141], off offset:64 nt
	global_load_dwordx4 v[206:209], v[142:143], off offset:512 nt
	global_load_dwordx4 v[210:213], v[140:141], off offset:512 nt
	global_load_dwordx4 v[214:217], v[142:143], off offset:576 nt
	global_load_dwordx4 v[218:221], v[140:141], off offset:576 nt
	v_lshlrev_b64 v[164:165], 11, v[162:163]
	v_lshlrev_b64 v[166:167], 11, v[134:135]
	v_lshl_add_u64 v[164:165], s[70:71], 0, v[164:165]
	v_lshlrev_b64 v[138:139], 1, v[138:139]
	v_lshl_add_u64 v[166:167], s[70:71], 0, v[166:167]
	v_lshl_add_u64 v[174:175], v[164:165], 0, v[138:139]
	v_lshl_add_u64 v[164:165], v[166:167], 0, v[138:139]
	s_lshl_b32 s10, s25, 2
	s_or_b32 s10, s10, s23
	s_waitcnt vmcnt(0)
	v_pk_fma_f32 v[122:123], s[90:91], v[122:123], v[196:197]
	v_pk_fma_f32 v[116:117], s[82:83], v[116:117], v[198:199]
	v_pk_fma_f32 v[126:127], s[90:91], v[126:127], v[192:193]
	v_pk_fma_f32 v[124:125], s[82:83], v[124:125], v[190:191]
	v_pk_fma_f32 v[112:113], s[82:83], v[112:113], v[202:203]
	v_pk_fma_f32 v[120:121], s[82:83], v[120:121], v[194:195]
	v_pk_fma_f32 v[118:119], s[90:91], v[118:119], v[200:201]
	v_pk_fma_f32 v[108:109], s[82:83], v[108:109], v[206:207]
	global_store_dwordx4 v[142:143], v[124:127], off nt
	global_store_dwordx4 v[140:141], v[120:123], off nt
	v_cvt_pk_bf16_f32 v166, v124, v125
	v_cvt_pk_bf16_f32 v167, v126, v127
	v_mul_f32_e32 v133, v117, v117
	v_mul_f32_e32 v173, v113, v113
	v_pk_fma_f32 v[114:115], s[90:91], v[114:115], v[204:205]
	v_mul_f32_e32 v181, v109, v109
	global_store_dwordx2 v[174:175], v[166:167], off
	v_cvt_pk_bf16_f32 v166, v120, v121
	v_cvt_pk_bf16_f32 v167, v122, v123
	v_fmac_f32_e32 v133, v116, v116
	v_fmac_f32_e32 v173, v112, v112
	global_store_dwordx2 v[164:165], v[166:167], off
	global_store_dwordx4 v[142:143], v[116:119], off offset:64 nt
	global_store_dwordx4 v[140:141], v[112:115], off offset:64 nt
	v_pk_fma_f32 v[110:111], s[90:91], v[110:111], v[208:209]
	v_cvt_pk_bf16_f32 v116, v116, v117
	v_cvt_pk_bf16_f32 v117, v118, v119
	global_store_dwordx2 v[174:175], v[116:117], off offset:32
	v_cvt_pk_bf16_f32 v112, v112, v113
	v_cvt_pk_bf16_f32 v113, v114, v115
	v_pk_fma_f32 v[106:107], s[90:91], v[106:107], v[212:213]
	v_pk_fma_f32 v[104:105], s[82:83], v[104:105], v[210:211]
	v_fmac_f32_e32 v181, v108, v108
	global_store_dwordx2 v[164:165], v[112:113], off offset:32
	global_store_dwordx4 v[142:143], v[108:111], off offset:512 nt
	global_store_dwordx4 v[140:141], v[104:107], off offset:512 nt
	v_mul_f32_e32 v129, v121, v121
	v_cvt_pk_bf16_f32 v108, v108, v109
	v_mul_f32_e32 v131, v123, v123
	v_mul_f32_e32 v177, v115, v115
	v_cvt_pk_bf16_f32 v109, v110, v111
	global_store_dwordx2 v[174:175], v[108:109], off offset:256
	v_cvt_pk_bf16_f32 v108, v104, v105
	v_mul_f32_e32 v105, v105, v105
	v_fmac_f32_e32 v129, v120, v120
	v_fmac_f32_e32 v131, v122, v122
	v_fmac_f32_e32 v177, v114, v114
	v_fmac_f32_e32 v105, v104, v104
	v_mul_f32_e32 v104, v107, v107
	v_mul_f32_e32 v148, v119, v119
	v_add_f32_e32 v121, v129, v131
	v_add_f32_e32 v119, v173, v177
	v_fmac_f32_e32 v104, v106, v106
	v_add_f32_e32 v115, v121, v119
	v_add_f32_e32 v104, v105, v104
	v_pk_fma_f32 v[102:103], s[90:91], v[102:103], v[216:217]
	v_pk_fma_f32 v[100:101], s[82:83], v[100:101], v[214:215]
	v_mul_f32_e32 v125, v125, v125
	v_mul_f32_e32 v127, v127, v127
	v_cvt_pk_bf16_f32 v109, v106, v107
	global_store_dwordx2 v[164:165], v[108:109], off offset:256
	v_add_f32_e32 v106, v115, v104
	v_pk_fma_f32 v[98:99], s[90:91], v[98:99], v[220:221]
	v_pk_fma_f32 v[96:97], s[82:83], v[96:97], v[218:219]
	global_store_dwordx4 v[142:143], v[100:103], off offset:576 nt
	global_store_dwordx4 v[140:141], v[96:99], off offset:576 nt
	v_cvt_pk_bf16_f32 v104, v100, v101
	v_mul_f32_e32 v183, v111, v111
	v_fmac_f32_e32 v125, v124, v124
	v_fmac_f32_e32 v127, v126, v126
	v_fmac_f32_e32 v148, v118, v118
	v_cvt_pk_bf16_f32 v105, v102, v103
	global_store_dwordx2 v[174:175], v[104:105], off offset:288
	v_cvt_pk_bf16_f32 v104, v96, v97
	v_mul_f32_e32 v101, v101, v101
	v_mul_f32_e32 v97, v97, v97
	v_fmac_f32_e32 v183, v110, v110
	v_add_f32_e32 v120, v125, v127
	v_add_f32_e32 v118, v133, v148
	v_fmac_f32_e32 v101, v100, v100
	v_mul_f32_e32 v100, v103, v103
	v_fmac_f32_e32 v97, v96, v96
	v_mul_f32_e32 v96, v99, v99
	v_add_f32_e32 v122, v181, v183
	v_add_f32_e32 v114, v120, v118
	v_fmac_f32_e32 v100, v102, v102
	v_fmac_f32_e32 v96, v98, v98
	v_add_f32_e32 v110, v114, v122
	v_add_f32_e32 v100, v101, v100
	v_add_f32_e32 v96, v97, v96
	v_cvt_pk_bf16_f32 v105, v98, v99
	v_add_f32_e32 v100, v110, v100
	v_add_f32_e32 v98, v106, v96
	v_mov_b32_e32 v96, v100
	v_mov_b32_e32 v99, v98
	s_nop 0
	v_permlane16_swap_b32_e32 v100, v96
	v_permlane16_swap_b32_e32 v98, v99
	v_add_f32_e32 v96, v100, v96
	v_add_f32_e32 v98, v98, v99
	v_mov_b32_e32 v97, v96
	v_mov_b32_e32 v99, v98
	s_nop 0
	v_permlane32_swap_b32_e32 v96, v97
	v_permlane32_swap_b32_e32 v98, v99
	global_store_dwordx2 v[164:165], v[104:105], off offset:288
	s_and_saveexec_b64 s[78:79], s[6:7]
	s_cbranch_execz .LBB0_543
	s_ashr_i32 s11, s10, 31
	v_lshlrev_b64 v[102:103], 6, v[162:163]
	v_lshlrev_b64 v[100:101], 6, v[134:135]
	s_lshl_b64 s[84:85], s[10:11], 2
	v_lshl_add_u64 v[102:103], s[38:39], 0, v[102:103]
	v_lshl_add_u64 v[100:101], s[38:39], 0, v[100:101]
	v_lshl_add_u64 v[102:103], v[102:103], 0, s[84:85]
	v_add_f32_e32 v96, v96, v97
	v_lshl_add_u64 v[100:101], v[100:101], 0, s[84:85]
	v_add_f32_e32 v98, v98, v99
	global_store_dword v[102:103], v96, off
	global_store_dword v[100:101], v98, off
.LBB0_543:
	s_or_b64 exec, exec, s[78:79]
	v_ashrrev_i32_e32 v131, 31, v130
	v_lshlrev_b64 v[96:97], 12, v[130:131]
	v_lshl_add_u64 v[96:97], s[16:17], 0, v[96:97]
	v_lshl_add_u64 v[98:99], v[96:97], 0, v[136:137]
	v_ashrrev_i32_e32 v133, 31, v132
	v_lshlrev_b64 v[96:97], 12, v[132:133]
	global_load_dwordx4 v[102:105], v[98:99], off nt
	v_lshl_add_u64 v[96:97], s[16:17], 0, v[96:97]
	v_lshl_add_u64 v[96:97], v[96:97], 0, v[136:137]
	global_load_dwordx4 v[106:109], v[96:97], off nt
	global_load_dwordx4 v[110:113], v[98:99], off offset:64 nt
	global_load_dwordx4 v[114:117], v[96:97], off offset:64 nt
	global_load_dwordx4 v[118:121], v[98:99], off offset:512 nt
	global_load_dwordx4 v[122:125], v[96:97], off offset:512 nt
	global_load_dwordx4 v[140:143], v[98:99], off offset:576 nt
	global_load_dwordx4 v[164:167], v[96:97], off offset:576 nt
	v_lshlrev_b64 v[100:101], 11, v[130:131]
	v_lshlrev_b64 v[126:127], 11, v[132:133]
	v_lshl_add_u64 v[100:101], s[70:71], 0, v[100:101]
	v_lshl_add_u64 v[126:127], s[70:71], 0, v[126:127]
	v_lshl_add_u64 v[134:135], v[100:101], 0, v[138:139]
	v_lshl_add_u64 v[100:101], v[126:127], 0, v[138:139]
	s_waitcnt vmcnt(0)
	v_pk_fma_f32 v[90:91], s[90:91], v[90:91], v[108:109]
	v_pk_fma_f32 v[84:85], s[82:83], v[84:85], v[110:111]
	v_pk_fma_f32 v[80:81], s[82:83], v[80:81], v[114:115]
	v_pk_fma_f32 v[94:95], s[90:91], v[94:95], v[104:105]
	v_pk_fma_f32 v[92:93], s[82:83], v[92:93], v[102:103]
	v_pk_fma_f32 v[88:89], s[82:83], v[88:89], v[106:107]
	v_pk_fma_f32 v[86:87], s[90:91], v[86:87], v[112:113]
	v_pk_fma_f32 v[76:77], s[82:83], v[76:77], v[118:119]
	v_pk_fma_f32 v[72:73], s[82:83], v[72:73], v[122:123]
	global_store_dwordx4 v[98:99], v[92:95], off nt
	global_store_dwordx4 v[96:97], v[88:91], off nt
	v_cvt_pk_bf16_f32 v102, v92, v93
	v_cvt_pk_bf16_f32 v103, v94, v95
	v_mul_f32_e32 v106, v85, v85
	v_mul_f32_e32 v108, v81, v81
	v_pk_fma_f32 v[82:83], s[90:91], v[82:83], v[116:117]
	v_mul_f32_e32 v110, v77, v77
	v_mul_f32_e32 v112, v73, v73
	global_store_dwordx2 v[134:135], v[102:103], off
	v_cvt_pk_bf16_f32 v102, v88, v89
	v_cvt_pk_bf16_f32 v103, v90, v91
	v_fmac_f32_e32 v106, v84, v84
	v_fmac_f32_e32 v108, v80, v80
	global_store_dwordx2 v[100:101], v[102:103], off
	global_store_dwordx4 v[98:99], v[84:87], off offset:64 nt
	global_store_dwordx4 v[96:97], v[80:83], off offset:64 nt
	v_pk_fma_f32 v[78:79], s[90:91], v[78:79], v[120:121]
	v_cvt_pk_bf16_f32 v84, v84, v85
	v_cvt_pk_bf16_f32 v85, v86, v87
	global_store_dwordx2 v[134:135], v[84:85], off offset:32
	v_cvt_pk_bf16_f32 v80, v80, v81
	v_cvt_pk_bf16_f32 v81, v82, v83
	v_pk_fma_f32 v[74:75], s[90:91], v[74:75], v[124:125]
	v_fmac_f32_e32 v110, v76, v76
	v_fmac_f32_e32 v112, v72, v72
	global_store_dwordx2 v[100:101], v[80:81], off offset:32
	global_store_dwordx4 v[98:99], v[76:79], off offset:512 nt
	global_store_dwordx4 v[96:97], v[72:75], off offset:512 nt
	v_pk_fma_f32 v[70:71], s[90:91], v[70:71], v[142:143]
	v_cvt_pk_bf16_f32 v76, v76, v77
	v_cvt_pk_bf16_f32 v77, v78, v79
	global_store_dwordx2 v[134:135], v[76:77], off offset:256
	v_cvt_pk_bf16_f32 v72, v72, v73
	v_pk_fma_f32 v[68:69], s[82:83], v[68:69], v[140:141]
	v_mul_f32_e32 v93, v93, v93
	v_mul_f32_e32 v95, v95, v95
	v_mul_f32_e32 v104, v89, v89
	v_mul_f32_e32 v105, v91, v91
	v_mul_f32_e32 v107, v87, v87
	v_mul_f32_e32 v109, v83, v83
	v_cvt_pk_bf16_f32 v73, v74, v75
	global_store_dwordx2 v[100:101], v[72:73], off offset:256
	v_pk_fma_f32 v[66:67], s[90:91], v[66:67], v[166:167]
	v_pk_fma_f32 v[64:65], s[82:83], v[64:65], v[164:165]
	global_store_dwordx4 v[98:99], v[68:71], off offset:576 nt
	global_store_dwordx4 v[96:97], v[64:67], off offset:576 nt
	v_cvt_pk_bf16_f32 v72, v68, v69
	v_mul_f32_e32 v111, v79, v79
	v_mul_f32_e32 v113, v75, v75
	v_fmac_f32_e32 v93, v92, v92
	v_fmac_f32_e32 v95, v94, v94
	v_fmac_f32_e32 v104, v88, v88
	v_fmac_f32_e32 v105, v90, v90
	v_fmac_f32_e32 v107, v86, v86
	v_fmac_f32_e32 v109, v82, v82
	v_cvt_pk_bf16_f32 v73, v70, v71
	global_store_dwordx2 v[134:135], v[72:73], off offset:288
	v_cvt_pk_bf16_f32 v72, v64, v65
	v_mul_f32_e32 v69, v69, v69
	v_mul_f32_e32 v65, v65, v65
	v_fmac_f32_e32 v111, v78, v78
	v_fmac_f32_e32 v113, v74, v74
	v_add_f32_e32 v88, v93, v95
	v_add_f32_e32 v89, v104, v105
	v_add_f32_e32 v86, v106, v107
	v_add_f32_e32 v87, v108, v109
	v_fmac_f32_e32 v69, v68, v68
	v_mul_f32_e32 v68, v71, v71
	v_fmac_f32_e32 v65, v64, v64
	v_mul_f32_e32 v64, v67, v67
	v_add_f32_e32 v90, v110, v111
	v_add_f32_e32 v91, v112, v113
	v_add_f32_e32 v82, v88, v86
	v_add_f32_e32 v83, v89, v87
	v_fmac_f32_e32 v68, v70, v70
	v_fmac_f32_e32 v64, v66, v66
	v_add_f32_e32 v78, v82, v90
	v_add_f32_e32 v74, v83, v91
	v_add_f32_e32 v68, v69, v68
	v_add_f32_e32 v64, v65, v64
	v_cvt_pk_bf16_f32 v73, v66, v67
	v_add_f32_e32 v68, v78, v68
	v_add_f32_e32 v66, v74, v64
	v_mov_b32_e32 v64, v68
	v_mov_b32_e32 v67, v66
	s_nop 0
	v_permlane16_swap_b32_e32 v68, v64
	v_permlane16_swap_b32_e32 v66, v67
	v_add_f32_e32 v64, v68, v64
	v_add_f32_e32 v66, v66, v67
	v_mov_b32_e32 v65, v64
	v_mov_b32_e32 v67, v66
	s_nop 0
	v_permlane32_swap_b32_e32 v64, v65
	v_permlane32_swap_b32_e32 v66, v67
	global_store_dwordx2 v[100:101], v[72:73], off offset:288
	s_and_saveexec_b64 s[78:79], s[6:7]
	s_cbranch_execz .LBB0_545
	s_ashr_i32 s11, s10, 31
	v_lshlrev_b64 v[70:71], 6, v[130:131]
	v_lshlrev_b64 v[68:69], 6, v[132:133]
	s_lshl_b64 s[84:85], s[10:11], 2
	v_lshl_add_u64 v[70:71], s[38:39], 0, v[70:71]
	v_lshl_add_u64 v[68:69], s[38:39], 0, v[68:69]
	v_lshl_add_u64 v[70:71], v[70:71], 0, s[84:85]
	v_add_f32_e32 v64, v64, v65
	v_lshl_add_u64 v[68:69], v[68:69], 0, s[84:85]
	v_add_f32_e32 v66, v66, v67
	global_store_dword v[70:71], v64, off
	global_store_dword v[68:69], v66, off
.LBB0_545:
	s_or_b64 exec, exec, s[78:79]
	v_ashrrev_i32_e32 v129, 31, v128
	v_lshlrev_b64 v[66:67], 12, v[128:129]
	v_lshl_add_u64 v[66:67], s[16:17], 0, v[66:67]
	v_add_u32_e32 v64, 0x90, v162
	v_lshl_add_u64 v[66:67], v[66:67], 0, v[136:137]
	v_ashrrev_i32_e32 v65, 31, v64
	global_load_dwordx4 v[74:77], v[66:67], off nt
	global_load_dwordx4 v[78:81], v[66:67], off offset:64 nt
	v_lshlrev_b64 v[68:69], 12, v[64:65]
	v_lshl_add_u64 v[68:69], s[16:17], 0, v[68:69]
	global_load_dwordx4 v[82:85], v[66:67], off offset:512 nt
	v_lshl_add_u64 v[68:69], v[68:69], 0, v[136:137]
	global_load_dwordx4 v[86:89], v[68:69], off nt
	global_load_dwordx4 v[90:93], v[68:69], off offset:64 nt
	global_load_dwordx4 v[94:97], v[68:69], off offset:512 nt
	global_load_dwordx4 v[98:101], v[66:67], off offset:576 nt
	global_load_dwordx4 v[102:105], v[68:69], off offset:576 nt
	v_lshlrev_b64 v[70:71], 11, v[128:129]
	v_lshl_add_u64 v[70:71], s[70:71], 0, v[70:71]
	v_lshlrev_b64 v[106:107], 11, v[64:65]
	v_lshl_add_u64 v[72:73], v[70:71], 0, v[138:139]
	v_lshl_add_u64 v[70:71], s[70:71], 0, v[106:107]
	v_lshl_add_u64 v[70:71], v[70:71], 0, v[138:139]
	s_waitcnt vmcnt(0)
	v_pk_fma_f32 v[62:63], s[90:91], v[62:63], v[76:77]
	v_pk_fma_f32 v[60:61], s[82:83], v[60:61], v[74:75]
	v_pk_fma_f32 v[54:55], s[90:91], v[54:55], v[88:89]
	v_pk_fma_f32 v[52:53], s[82:83], v[52:53], v[86:87]
	v_mul_f32_e32 v77, v63, v63
	v_pk_fma_f32 v[48:49], s[82:83], v[48:49], v[90:91]
	v_pk_fma_f32 v[58:59], s[90:91], v[58:59], v[80:81]
	v_pk_fma_f32 v[56:57], s[82:83], v[56:57], v[78:79]
	v_pk_fma_f32 v[44:45], s[82:83], v[44:45], v[82:83]
	global_store_dwordx4 v[66:67], v[60:63], off nt
	v_mul_f32_e32 v76, v61, v61
	v_pk_fma_f32 v[40:41], s[82:83], v[40:41], v[94:95]
	global_store_dwordx4 v[68:69], v[52:55], off nt
	v_cvt_pk_bf16_f32 v74, v60, v61
	v_cvt_pk_bf16_f32 v75, v62, v63
	v_fmac_f32_e32 v77, v62, v62
	v_mul_f32_e32 v62, v53, v53
	v_mul_f32_e32 v82, v49, v49
	v_pk_fma_f32 v[46:47], s[90:91], v[46:47], v[84:85]
	v_pk_fma_f32 v[50:51], s[90:91], v[50:51], v[92:93]
	v_mul_f32_e32 v80, v45, v45
	v_fmac_f32_e32 v76, v60, v60
	v_mul_f32_e32 v84, v41, v41
	global_store_dwordx2 v[72:73], v[74:75], off
	v_cvt_pk_bf16_f32 v60, v52, v53
	v_cvt_pk_bf16_f32 v61, v54, v55
	v_fmac_f32_e32 v62, v52, v52
	v_fmac_f32_e32 v82, v48, v48
	global_store_dwordx2 v[70:71], v[60:61], off
	global_store_dwordx4 v[66:67], v[56:59], off offset:64 nt
	global_store_dwordx4 v[68:69], v[48:51], off offset:64 nt
	v_cvt_pk_bf16_f32 v52, v56, v57
	v_cvt_pk_bf16_f32 v53, v58, v59
	global_store_dwordx2 v[72:73], v[52:53], off offset:32
	v_mul_f32_e32 v78, v57, v57
	v_cvt_pk_bf16_f32 v48, v48, v49
	v_cvt_pk_bf16_f32 v49, v50, v51
	v_mul_f32_e32 v79, v59, v59
	v_pk_fma_f32 v[42:43], s[90:91], v[42:43], v[96:97]
	v_fmac_f32_e32 v80, v44, v44
	v_fmac_f32_e32 v84, v40, v40
	global_store_dwordx2 v[70:71], v[48:49], off offset:32
	global_store_dwordx4 v[66:67], v[44:47], off offset:512 nt
	global_store_dwordx4 v[68:69], v[40:43], off offset:512 nt
	v_pk_fma_f32 v[38:39], s[90:91], v[38:39], v[100:101]
	v_cvt_pk_bf16_f32 v44, v44, v45
	v_cvt_pk_bf16_f32 v45, v46, v47
	global_store_dwordx2 v[72:73], v[44:45], off offset:256
	v_cvt_pk_bf16_f32 v40, v40, v41
	v_pk_fma_f32 v[36:37], s[82:83], v[36:37], v[98:99]
	v_mul_f32_e32 v63, v55, v55
	v_fmac_f32_e32 v78, v56, v56
	v_fmac_f32_e32 v79, v58, v58
	v_mul_f32_e32 v83, v51, v51
	v_cvt_pk_bf16_f32 v41, v42, v43
	global_store_dwordx2 v[70:71], v[40:41], off offset:256
	v_pk_fma_f32 v[34:35], s[90:91], v[34:35], v[104:105]
	v_pk_fma_f32 v[32:33], s[82:83], v[32:33], v[102:103]
	global_store_dwordx4 v[66:67], v[36:39], off offset:576 nt
	global_store_dwordx4 v[68:69], v[32:35], off offset:576 nt
	v_cvt_pk_bf16_f32 v40, v36, v37
	v_mul_f32_e32 v81, v47, v47
	v_mul_f32_e32 v85, v43, v43
	v_add_f32_e32 v55, v76, v77
	v_fmac_f32_e32 v63, v54, v54
	v_add_f32_e32 v54, v78, v79
	v_fmac_f32_e32 v83, v50, v50
	v_cvt_pk_bf16_f32 v41, v38, v39
	global_store_dwordx2 v[72:73], v[40:41], off offset:288
	v_cvt_pk_bf16_f32 v40, v32, v33
	v_mul_f32_e32 v37, v37, v37
	v_mul_f32_e32 v33, v33, v33
	v_fmac_f32_e32 v81, v46, v46
	v_fmac_f32_e32 v85, v42, v42
	v_add_f32_e32 v60, v62, v63
	v_add_f32_e32 v54, v55, v54
	v_add_f32_e32 v55, v82, v83
	v_fmac_f32_e32 v37, v36, v36
	v_mul_f32_e32 v36, v39, v39
	v_fmac_f32_e32 v33, v32, v32
	v_mul_f32_e32 v32, v35, v35
	v_add_f32_e32 v74, v80, v81
	v_add_f32_e32 v56, v84, v85
	v_add_f32_e32 v50, v60, v55
	v_fmac_f32_e32 v36, v38, v38
	v_fmac_f32_e32 v32, v34, v34
	v_add_f32_e32 v51, v54, v74
	v_add_f32_e32 v42, v50, v56
	v_add_f32_e32 v36, v37, v36
	v_add_f32_e32 v32, v33, v32
	v_cvt_pk_bf16_f32 v41, v34, v35
	v_add_f32_e32 v36, v51, v36
	v_add_f32_e32 v34, v42, v32
	v_mov_b32_e32 v32, v36
	v_mov_b32_e32 v35, v34
	s_nop 0
	v_permlane16_swap_b32_e32 v36, v32
	v_permlane16_swap_b32_e32 v34, v35
	v_add_f32_e32 v32, v36, v32
	v_add_f32_e32 v34, v34, v35
	v_mov_b32_e32 v33, v32
	v_mov_b32_e32 v35, v34
	s_nop 0
	v_permlane32_swap_b32_e32 v32, v33
	v_permlane32_swap_b32_e32 v34, v35
	global_store_dwordx2 v[70:71], v[40:41], off offset:288
	s_and_saveexec_b64 s[78:79], s[6:7]
	s_cbranch_execz .LBB0_547
	s_ashr_i32 s11, s10, 31
	v_lshlrev_b64 v[38:39], 6, v[128:129]
	v_lshlrev_b64 v[36:37], 6, v[64:65]
	s_lshl_b64 s[84:85], s[10:11], 2
	v_lshl_add_u64 v[38:39], s[38:39], 0, v[38:39]
	v_lshl_add_u64 v[36:37], s[38:39], 0, v[36:37]
	v_lshl_add_u64 v[38:39], v[38:39], 0, s[84:85]
	v_add_f32_e32 v32, v32, v33
	v_lshl_add_u64 v[36:37], v[36:37], 0, s[84:85]
	v_add_f32_e32 v34, v34, v35
	global_store_dword v[38:39], v32, off
	global_store_dword v[36:37], v34, off
.LBB0_547:
	s_or_b64 exec, exec, s[78:79]
	v_add_u32_e32 v32, 0xa0, v162
	v_ashrrev_i32_e32 v33, 31, v32
	v_lshlrev_b64 v[36:37], 12, v[32:33]
	v_add_u32_e32 v34, 0xb0, v162
	v_lshl_add_u64 v[36:37], s[16:17], 0, v[36:37]
	v_lshl_add_u64 v[38:39], v[36:37], 0, v[136:137]
	v_ashrrev_i32_e32 v35, 31, v34
	v_lshlrev_b64 v[36:37], 12, v[34:35]
	global_load_dwordx4 v[42:45], v[38:39], off nt
	v_lshl_add_u64 v[36:37], s[16:17], 0, v[36:37]
	v_lshl_add_u64 v[36:37], v[36:37], 0, v[136:137]
	global_load_dwordx4 v[46:49], v[36:37], off nt
	global_load_dwordx4 v[50:53], v[38:39], off offset:64 nt
	global_load_dwordx4 v[54:57], v[36:37], off offset:64 nt
	global_load_dwordx4 v[58:61], v[38:39], off offset:512 nt
	global_load_dwordx4 v[62:65], v[36:37], off offset:512 nt
	global_load_dwordx4 v[66:69], v[38:39], off offset:576 nt
	global_load_dwordx4 v[70:73], v[36:37], off offset:576 nt
	v_lshlrev_b64 v[40:41], 11, v[32:33]
	v_lshlrev_b64 v[74:75], 11, v[34:35]
	v_lshl_add_u64 v[40:41], s[70:71], 0, v[40:41]
	v_lshl_add_u64 v[74:75], s[70:71], 0, v[74:75]
	v_lshl_add_u64 v[76:77], v[40:41], 0, v[138:139]
	v_lshl_add_u64 v[40:41], v[74:75], 0, v[138:139]
	s_waitcnt vmcnt(0)
	v_pk_fma_f32 v[26:27], s[90:91], v[26:27], v[48:49]
	v_pk_fma_f32 v[24:25], s[82:83], v[24:25], v[46:47]
	v_pk_fma_f32 v[20:21], s[82:83], v[20:21], v[50:51]
	v_pk_fma_f32 v[30:31], s[90:91], v[30:31], v[44:45]
	v_pk_fma_f32 v[28:29], s[82:83], v[28:29], v[42:43]
	v_pk_fma_f32 v[18:19], s[90:91], v[18:19], v[56:57]
	v_pk_fma_f32 v[16:17], s[82:83], v[16:17], v[54:55]
	v_pk_fma_f32 v[22:23], s[90:91], v[22:23], v[52:53]
	v_pk_fma_f32 v[12:13], s[82:83], v[12:13], v[58:59]
	v_pk_fma_f32 v[10:11], s[90:91], v[10:11], v[64:65]
	v_pk_fma_f32 v[8:9], s[82:83], v[8:9], v[62:63]
	global_store_dwordx4 v[38:39], v[28:31], off nt
	global_store_dwordx4 v[36:37], v[24:27], off nt
	v_cvt_pk_bf16_f32 v42, v28, v29
	v_cvt_pk_bf16_f32 v43, v30, v31
	v_mul_f32_e32 v44, v25, v25
	v_mul_f32_e32 v45, v27, v27
	v_mul_f32_e32 v46, v21, v21
	v_mul_f32_e32 v48, v17, v17
	v_mul_f32_e32 v49, v19, v19
	v_mul_f32_e32 v50, v13, v13
	v_mul_f32_e32 v52, v9, v9
	v_mul_f32_e32 v53, v11, v11
	global_store_dwordx2 v[76:77], v[42:43], off
	v_cvt_pk_bf16_f32 v42, v24, v25
	v_cvt_pk_bf16_f32 v43, v26, v27
	v_fmac_f32_e32 v44, v24, v24
	v_fmac_f32_e32 v45, v26, v26
	v_fmac_f32_e32 v46, v20, v20
	v_fmac_f32_e32 v48, v16, v16
	v_fmac_f32_e32 v49, v18, v18
	global_store_dwordx2 v[40:41], v[42:43], off
	global_store_dwordx4 v[38:39], v[20:23], off offset:64 nt
	global_store_dwordx4 v[36:37], v[16:19], off offset:64 nt
	v_pk_fma_f32 v[14:15], s[90:91], v[14:15], v[60:61]
	v_cvt_pk_bf16_f32 v20, v20, v21
	v_cvt_pk_bf16_f32 v21, v22, v23
	global_store_dwordx2 v[76:77], v[20:21], off offset:32
	v_cvt_pk_bf16_f32 v16, v16, v17
	v_cvt_pk_bf16_f32 v17, v18, v19
	v_mul_f32_e32 v47, v23, v23
	v_fmac_f32_e32 v50, v12, v12
	v_fmac_f32_e32 v52, v8, v8
	v_fmac_f32_e32 v53, v10, v10
	v_add_f32_e32 v25, v44, v45
	v_add_f32_e32 v23, v48, v49
	global_store_dwordx2 v[40:41], v[16:17], off offset:32
	global_store_dwordx4 v[38:39], v[12:15], off offset:512 nt
	global_store_dwordx4 v[36:37], v[8:11], off offset:512 nt
	v_add_f32_e32 v19, v25, v23
	v_cvt_pk_bf16_f32 v12, v12, v13
	v_cvt_pk_bf16_f32 v13, v14, v15
	global_store_dwordx2 v[76:77], v[12:13], off offset:256
	v_cvt_pk_bf16_f32 v8, v8, v9
	v_cvt_pk_bf16_f32 v9, v10, v11
	global_store_dwordx2 v[40:41], v[8:9], off offset:256
	v_add_f32_e32 v8, v52, v53
	v_pk_fma_f32 v[6:7], s[90:91], v[6:7], v[68:69]
	v_pk_fma_f32 v[4:5], s[82:83], v[4:5], v[66:67]
	v_mul_f32_e32 v29, v29, v29
	v_mul_f32_e32 v31, v31, v31
	v_add_f32_e32 v10, v19, v8
	v_pk_fma_f32 v[2:3], s[90:91], v[2:3], v[72:73]
	v_pk_fma_f32 v[0:1], s[82:83], v[0:1], v[70:71]
	global_store_dwordx4 v[38:39], v[4:7], off offset:576 nt
	global_store_dwordx4 v[36:37], v[0:3], off offset:576 nt
	v_cvt_pk_bf16_f32 v8, v4, v5
	v_mul_f32_e32 v51, v15, v15
	v_fmac_f32_e32 v29, v28, v28
	v_fmac_f32_e32 v31, v30, v30
	v_fmac_f32_e32 v47, v22, v22
	v_cvt_pk_bf16_f32 v9, v6, v7
	global_store_dwordx2 v[76:77], v[8:9], off offset:288
	v_cvt_pk_bf16_f32 v8, v0, v1
	v_mul_f32_e32 v5, v5, v5
	v_mul_f32_e32 v1, v1, v1
	v_fmac_f32_e32 v51, v14, v14
	v_add_f32_e32 v24, v29, v31
	v_add_f32_e32 v22, v46, v47
	v_fmac_f32_e32 v5, v4, v4
	v_mul_f32_e32 v4, v7, v7
	v_fmac_f32_e32 v1, v0, v0
	v_mul_f32_e32 v0, v3, v3
	v_add_f32_e32 v26, v50, v51
	v_add_f32_e32 v18, v24, v22
	v_fmac_f32_e32 v4, v6, v6
	v_fmac_f32_e32 v0, v2, v2
	v_add_f32_e32 v14, v18, v26
	v_add_f32_e32 v4, v5, v4
	v_add_f32_e32 v0, v1, v0
	v_cvt_pk_bf16_f32 v9, v2, v3
	v_add_f32_e32 v4, v14, v4
	v_add_f32_e32 v2, v10, v0
	v_mov_b32_e32 v0, v4
	v_mov_b32_e32 v3, v2
	s_nop 0
	v_permlane16_swap_b32_e32 v4, v0
	v_permlane16_swap_b32_e32 v2, v3
	v_add_f32_e32 v0, v4, v0
	v_add_f32_e32 v2, v2, v3
	v_mov_b32_e32 v1, v0
	v_mov_b32_e32 v3, v2
	s_nop 0
	v_permlane32_swap_b32_e32 v0, v1
	v_permlane32_swap_b32_e32 v2, v3
	global_store_dwordx2 v[40:41], v[8:9], off offset:288
	s_and_saveexec_b64 s[78:79], s[6:7]
	s_cbranch_execz .LBB0_513
	s_ashr_i32 s11, s10, 31
	v_lshlrev_b64 v[6:7], 6, v[32:33]
	v_lshlrev_b64 v[4:5], 6, v[34:35]
	s_lshl_b64 s[10:11], s[10:11], 2
	v_lshl_add_u64 v[6:7], s[38:39], 0, v[6:7]
	v_lshl_add_u64 v[4:5], s[38:39], 0, v[4:5]
	v_lshl_add_u64 v[6:7], v[6:7], 0, s[10:11]
	v_add_f32_e32 v0, v0, v1
	v_lshl_add_u64 v[4:5], v[4:5], 0, s[10:11]
	v_add_f32_e32 v2, v2, v3
	global_store_dword v[6:7], v0, off
	global_store_dword v[4:5], v2, off
	s_branch .LBB0_513
